# latent-attention fused loop: next operand LDS read issued ahead of the wait/MFMA of each step
# baseline (speedup 1.0000x reference)
.LBB0_86:
	s_mul_i32 s14, s9, 0x6400
	v_add_u32_e32 v174, s14, v167
	ds_read_b128 v[66:69], v174 offset:25600
	ds_read_b128 v[70:73], v174 offset:25632
	ds_read_b128 v[74:77], v174 offset:25664
	v_add_u32_e32 v175, s8, v168
	ds_read_b128 v[78:81], v174 offset:25696
	s_waitcnt lgkmcnt(3)
	v_mfma_f32_32x32x16_bf16 v[82:97], v[66:69], v[110:113], 0
	v_exp_f32_e32 v50, v50
	v_exp_f32_e32 v51, v51
	ds_read_b128 v[66:69], v174 offset:25728
	s_waitcnt lgkmcnt(3)
	v_mfma_f32_32x32x16_bf16 v[82:97], v[70:73], v[114:117], v[82:97]
	v_exp_f32_e32 v52, v52
	v_exp_f32_e32 v53, v53
	ds_read_b128 v[70:73], v174 offset:25760
	s_waitcnt lgkmcnt(3)
	v_mfma_f32_32x32x16_bf16 v[82:97], v[74:77], v[118:121], v[82:97]
	v_exp_f32_e32 v54, v54
	v_exp_f32_e32 v55, v55
	v_pk_add_f32 v[176:177], v[50:51], 0 op_sel_hi:[1,0]
	ds_read_b128 v[74:77], v174 offset:32256
	s_waitcnt lgkmcnt(3)
	v_mfma_f32_32x32x16_bf16 v[82:97], v[78:81], v[122:125], v[82:97]
	v_exp_f32_e32 v56, v56
	v_exp_f32_e32 v57, v57
	v_pk_add_f32 v[78:79], v[52:53], v[176:177]
	ds_read_b128 v[176:179], v174 offset:32288
	s_waitcnt lgkmcnt(3)
	v_mfma_f32_32x32x16_bf16 v[82:97], v[66:69], v[126:129], v[82:97]
	v_exp_f32_e32 v58, v58
	v_exp_f32_e32 v59, v59
	v_pk_add_f32 v[66:67], v[54:55], v[78:79]
	ds_read_b128 v[180:183], v174 offset:32320
	s_waitcnt lgkmcnt(3)
	v_mfma_f32_32x32x16_bf16 v[82:97], v[70:73], v[130:133], v[82:97]
	v_exp_f32_e32 v60, v60
	v_exp_f32_e32 v61, v61
	v_pk_add_f32 v[190:191], v[56:57], v[66:67]
	ds_read_b128 v[184:187], v174 offset:32352
	s_waitcnt lgkmcnt(3)
	v_mfma_f32_32x32x16_bf16 v[66:81], v[74:77], v[110:113], 0
	v_exp_f32_e32 v62, v62
	v_exp_f32_e32 v63, v63
	v_pk_add_f32 v[194:195], v[58:59], v[190:191]
	ds_read_b128 v[190:193], v174 offset:32384
	s_waitcnt lgkmcnt(3)
	v_mfma_f32_32x32x16_bf16 v[66:81], v[176:179], v[114:117], v[66:81]
	v_exp_f32_e32 v64, v64
	v_exp_f32_e32 v65, v65
	v_pk_add_f32 v[194:195], v[60:61], v[194:195]
	ds_read_b128 v[176:179], v174 offset:32416
	s_waitcnt lgkmcnt(3)
	v_mfma_f32_32x32x16_bf16 v[66:81], v[180:183], v[118:121], v[66:81]
	v_exp_f32_e32 v34, v34
	v_exp_f32_e32 v35, v35
	v_pk_add_f32 v[194:195], v[62:63], v[194:195]
	ds_read_b64_tr_b16 v[180:181], v175 offset:13312
	ds_read_b64_tr_b16 v[182:183], v175 offset:14848
	s_waitcnt lgkmcnt(4)
	v_mfma_f32_32x32x16_bf16 v[66:81], v[184:187], v[122:125], v[66:81]
	v_exp_f32_e32 v36, v36
	v_exp_f32_e32 v37, v37
	v_pk_add_f32 v[194:195], v[64:65], v[194:195]
	ds_read_b64_tr_b16 v[184:185], v175 offset:13376
	ds_read_b64_tr_b16 v[186:187], v175 offset:14912
	s_waitcnt lgkmcnt(5)
	v_mfma_f32_32x32x16_bf16 v[66:81], v[190:193], v[126:129], v[66:81]
	v_exp_f32_e32 v38, v38
	v_exp_f32_e32 v39, v39
	v_pk_add_f32 v[194:195], v[34:35], v[194:195]
	ds_read_b64_tr_b16 v[190:191], v175 offset:16384
	ds_read_b64_tr_b16 v[192:193], v175 offset:17920
	s_waitcnt lgkmcnt(6)
	v_mfma_f32_32x32x16_bf16 v[66:81], v[176:179], v[130:133], v[66:81]
	v_exp_f32_e32 v40, v40
	v_exp_f32_e32 v41, v41
	v_pk_add_f32 v[194:195], v[36:37], v[194:195]
	ds_read_b64_tr_b16 v[176:177], v175 offset:16448
	ds_read_b64_tr_b16 v[178:179], v175 offset:17984
	s_waitcnt lgkmcnt(6)
	v_mfma_f32_32x32x16_bf16 v[2:17], v[180:183], v[142:145], v[2:17]
	v_exp_f32_e32 v42, v42
	v_exp_f32_e32 v43, v43
	v_pk_add_f32 v[194:195], v[38:39], v[194:195]
	ds_read_b64_tr_b16 v[180:181], v175 offset:19456
	ds_read_b64_tr_b16 v[182:183], v175 offset:20992
	s_waitcnt lgkmcnt(6)
	v_mfma_f32_32x32x16_bf16 v[18:33], v[184:187], v[142:145], v[18:33]
	v_exp_f32_e32 v44, v44
	v_exp_f32_e32 v45, v45
	v_pk_add_f32 v[184:185], v[40:41], v[194:195]
	ds_read_b64_tr_b16 v[142:143], v175 offset:19520
	ds_read_b64_tr_b16 v[144:145], v175 offset:21056
	s_waitcnt lgkmcnt(6)
	v_mfma_f32_32x32x16_bf16 v[2:17], v[190:193], v[146:149], v[2:17]
	v_exp_f32_e32 v46, v46
	v_exp_f32_e32 v47, v47
	v_pk_add_f32 v[190:191], v[42:43], v[184:185]
	ds_read_b64_tr_b16 v[184:185], v175 offset:22528
	ds_read_b64_tr_b16 v[186:187], v175 offset:24064
	s_waitcnt lgkmcnt(6)
	v_mfma_f32_32x32x16_bf16 v[18:33], v[176:179], v[146:149], v[18:33]
	v_exp_f32_e32 v48, v48
	v_exp_f32_e32 v49, v49
	v_pk_add_f32 v[176:177], v[44:45], v[190:191]
	ds_read_b64_tr_b16 v[146:147], v175 offset:22592
	ds_read_b64_tr_b16 v[148:149], v175 offset:24128
	s_waitcnt lgkmcnt(6)
	v_mfma_f32_32x32x16_bf16 v[2:17], v[180:183], v[134:137], v[2:17]
	v_add_f32_e64 v176, v46, v176
	v_add_f32_e64 v177, v47, v177
	s_waitcnt lgkmcnt(4)
	v_mfma_f32_32x32x16_bf16 v[18:33], v[142:145], v[134:137], v[18:33]
	v_add_f32_e64 v134, v48, v176
	v_add_f32_e64 v135, v49, v177
	s_waitcnt lgkmcnt(2)
	v_mfma_f32_32x32x16_bf16 v[2:17], v[184:187], v[138:141], v[2:17]
	s_waitcnt lgkmcnt(0)
	v_mfma_f32_32x32x16_bf16 v[18:33], v[146:149], v[138:141], v[18:33]
	v_add_f32_e32 v175, v134, v135
	v_cmp_ngt_f32_e32 vcc, s82, v175
	s_cbranch_vccz .LBB0_88
	ds_read_b128 v[34:37], v174
	ds_read_b128 v[50:53], v174 offset:32
	s_mov_b64 s[12:13], 0
	s_waitcnt lgkmcnt(1)
	v_mfma_f32_32x32x16_bf16 v[34:49], v[34:37], v[110:113], 0
	s_waitcnt lgkmcnt(0)
	v_mfma_f32_32x32x16_bf16 v[34:49], v[50:53], v[114:117], v[34:49]
	ds_read_b128 v[50:53], v174 offset:64
	ds_read_b128 v[54:57], v174 offset:96
	s_waitcnt lgkmcnt(1)
	v_mfma_f32_32x32x16_bf16 v[34:49], v[50:53], v[118:121], v[34:49]
	s_waitcnt lgkmcnt(0)
	v_mfma_f32_32x32x16_bf16 v[34:49], v[54:57], v[122:125], v[34:49]
	ds_read_b128 v[50:53], v174 offset:128
	ds_read_b128 v[54:57], v174 offset:160
	s_waitcnt lgkmcnt(1)
	v_mfma_f32_32x32x16_bf16 v[34:49], v[50:53], v[126:129], v[34:49]
	ds_read_b128 v[50:53], v174 offset:6656
	ds_read_b128 v[134:137], v174 offset:6688
	s_waitcnt lgkmcnt(2)
	v_mfma_f32_32x32x16_bf16 v[34:49], v[54:57], v[130:133], v[34:49]
	s_waitcnt lgkmcnt(1)
	v_mfma_f32_32x32x16_bf16 v[50:65], v[50:53], v[110:113], 0
	s_nop 9
	v_max3_f32 v142, v34, s33, v35
	s_waitcnt lgkmcnt(0)
	v_mfma_f32_32x32x16_bf16 v[50:65], v[134:137], v[114:117], v[50:65]
	ds_read_b128 v[134:137], v174 offset:6720
	ds_read_b128 v[138:141], v174 offset:6752
	s_waitcnt lgkmcnt(1)
	v_mfma_f32_32x32x16_bf16 v[50:65], v[134:137], v[118:121], v[50:65]
	s_waitcnt lgkmcnt(0)
	v_mfma_f32_32x32x16_bf16 v[50:65], v[138:141], v[122:125], v[50:65]
	ds_read_b128 v[134:137], v174 offset:6784
	ds_read_b128 v[138:141], v174 offset:6816
	s_waitcnt lgkmcnt(1)
	v_mfma_f32_32x32x16_bf16 v[50:65], v[134:137], v[126:129], v[50:65]
	v_max3_f32 v134, v142, v36, v37
	v_max3_f32 v134, v134, v38, v39
	v_max3_f32 v134, v134, v40, v41
	v_max3_f32 v134, v134, v42, v43
	v_max3_f32 v134, v134, v44, v45
	v_max3_f32 v134, v134, v46, v47
	v_max3_f32 v134, v134, v48, v49
	s_waitcnt lgkmcnt(0)
	v_mfma_f32_32x32x16_bf16 v[50:65], v[138:141], v[130:133], v[50:65]
	v_mov_b32_e32 v135, v220
	s_nop 0
	v_lshlrev_b32_e32 v135, 2, v135
	v_xor_b32_e32 v135, 0x80, v135
	s_nop 7
	v_max3_f32 v134, v134, v50, v51
	v_max3_f32 v134, v134, v52, v53
	v_max3_f32 v134, v134, v54, v55
	v_max3_f32 v134, v134, v56, v57
	v_max3_f32 v134, v134, v58, v59
	v_max3_f32 v134, v134, v60, v61
	v_max3_f32 v134, v134, v62, v63
	v_max3_f32 v134, v134, v64, v65
	ds_bpermute_b32 v135, v135, v134
	s_waitcnt lgkmcnt(0)
	v_max3_f32 v176, v164, v134, v135
	v_pk_add_f32 v[34:35], v[34:35], v[176:177] op_sel_hi:[1,0] neg_lo:[0,1] neg_hi:[0,1]
	v_pk_add_f32 v[36:37], v[36:37], v[176:177] op_sel_hi:[1,0] neg_lo:[0,1] neg_hi:[0,1]
	v_exp_f32_e32 v34, v34
	v_exp_f32_e32 v35, v35
	v_pk_add_f32 v[38:39], v[38:39], v[176:177] op_sel_hi:[1,0] neg_lo:[0,1] neg_hi:[0,1]
	v_exp_f32_e32 v36, v36
	v_exp_f32_e32 v37, v37
	v_pk_add_f32 v[40:41], v[40:41], v[176:177] op_sel_hi:[1,0] neg_lo:[0,1] neg_hi:[0,1]
	v_exp_f32_e32 v38, v38
	v_exp_f32_e32 v39, v39
	v_sub_f32_e32 v134, v164, v176
	v_pk_add_f32 v[42:43], v[42:43], v[176:177] op_sel_hi:[1,0] neg_lo:[0,1] neg_hi:[0,1]
	v_exp_f32_e32 v40, v40
	v_exp_f32_e32 v41, v41
	v_exp_f32_e32 v164, v134
	v_pk_add_f32 v[44:45], v[44:45], v[176:177] op_sel_hi:[1,0] neg_lo:[0,1] neg_hi:[0,1]
	v_exp_f32_e32 v42, v42
	v_exp_f32_e32 v43, v43
	v_pk_add_f32 v[134:135], v[34:35], 0 op_sel_hi:[1,0]
	v_pk_add_f32 v[46:47], v[46:47], v[176:177] op_sel_hi:[1,0] neg_lo:[0,1] neg_hi:[0,1]
	v_exp_f32_e32 v44, v44
	v_exp_f32_e32 v45, v45
	v_cvt_pk_bf16_f32 v146, v34, v35
	v_pk_add_f32 v[34:35], v[36:37], v[134:135]
	v_pk_add_f32 v[48:49], v[48:49], v[176:177] op_sel_hi:[1,0] neg_lo:[0,1] neg_hi:[0,1]
	v_exp_f32_e32 v46, v46
	v_exp_f32_e32 v47, v47
	v_pk_add_f32 v[34:35], v[38:39], v[34:35]
	v_pk_add_f32 v[50:51], v[50:51], v[176:177] op_sel_hi:[1,0] neg_lo:[0,1] neg_hi:[0,1]
	v_exp_f32_e32 v48, v48
	v_exp_f32_e32 v49, v49
	v_pk_add_f32 v[34:35], v[40:41], v[34:35]
	v_pk_add_f32 v[52:53], v[52:53], v[176:177] op_sel_hi:[1,0] neg_lo:[0,1] neg_hi:[0,1]
	v_exp_f32_e32 v50, v50
	v_exp_f32_e32 v51, v51
	v_pk_add_f32 v[34:35], v[42:43], v[34:35]
	v_pk_add_f32 v[54:55], v[54:55], v[176:177] op_sel_hi:[1,0] neg_lo:[0,1] neg_hi:[0,1]
	v_exp_f32_e32 v52, v52
	v_exp_f32_e32 v53, v53
	v_pk_add_f32 v[34:35], v[44:45], v[34:35]
	v_pk_add_f32 v[56:57], v[56:57], v[176:177] op_sel_hi:[1,0] neg_lo:[0,1] neg_hi:[0,1]
	v_exp_f32_e32 v54, v54
	v_exp_f32_e32 v55, v55
	v_pk_add_f32 v[34:35], v[46:47], v[34:35]
	v_pk_add_f32 v[58:59], v[58:59], v[176:177] op_sel_hi:[1,0] neg_lo:[0,1] neg_hi:[0,1]
	v_exp_f32_e32 v56, v56
	v_exp_f32_e32 v57, v57
	v_pk_add_f32 v[34:35], v[48:49], v[34:35]
	v_pk_add_f32 v[60:61], v[60:61], v[176:177] op_sel_hi:[1,0] neg_lo:[0,1] neg_hi:[0,1]
	v_exp_f32_e32 v58, v58
	v_exp_f32_e32 v59, v59
	v_pk_add_f32 v[34:35], v[50:51], v[34:35]
	v_pk_add_f32 v[62:63], v[62:63], v[176:177] op_sel_hi:[1,0] neg_lo:[0,1] neg_hi:[0,1]
	v_exp_f32_e32 v60, v60
	v_exp_f32_e32 v61, v61
	v_pk_add_f32 v[34:35], v[52:53], v[34:35]
	v_pk_add_f32 v[64:65], v[64:65], v[176:177] op_sel_hi:[1,0] neg_lo:[0,1] neg_hi:[0,1]
	v_exp_f32_e32 v62, v62
	v_exp_f32_e32 v63, v63
	v_pk_add_f32 v[34:35], v[54:55], v[34:35]
	v_exp_f32_e32 v64, v64
	v_exp_f32_e32 v65, v65
	v_pk_add_f32 v[34:35], v[56:57], v[34:35]
	v_pk_mul_f32 v[16:17], v[16:17], v[164:165] op_sel_hi:[1,0]
	v_pk_add_f32 v[34:35], v[58:59], v[34:35]
	v_pk_mul_f32 v[14:15], v[14:15], v[164:165] op_sel_hi:[1,0]
	v_pk_add_f32 v[34:35], v[60:61], v[34:35]
	v_pk_mul_f32 v[12:13], v[12:13], v[164:165] op_sel_hi:[1,0]
	v_pk_add_f32 v[34:35], v[62:63], v[34:35]
	v_pk_mul_f32 v[10:11], v[10:11], v[164:165] op_sel_hi:[1,0]
	v_pk_add_f32 v[34:35], v[64:65], v[34:35]
	v_pk_mul_f32 v[8:9], v[8:9], v[164:165] op_sel_hi:[1,0]
	v_pk_mul_f32 v[6:7], v[6:7], v[164:165] op_sel_hi:[1,0]
	v_pk_mul_f32 v[4:5], v[4:5], v[164:165] op_sel_hi:[1,0]
	v_pk_mul_f32 v[2:3], v[2:3], v[164:165] op_sel_hi:[1,0]
	v_pk_mul_f32 v[32:33], v[32:33], v[164:165] op_sel_hi:[1,0]
	v_pk_mul_f32 v[30:31], v[30:31], v[164:165] op_sel_hi:[1,0]
	v_pk_mul_f32 v[28:29], v[28:29], v[164:165] op_sel_hi:[1,0]
	v_pk_mul_f32 v[26:27], v[26:27], v[164:165] op_sel_hi:[1,0]
	v_pk_mul_f32 v[24:25], v[24:25], v[164:165] op_sel_hi:[1,0]
	v_pk_mul_f32 v[22:23], v[22:23], v[164:165] op_sel_hi:[1,0]
	v_pk_mul_f32 v[20:21], v[20:21], v[164:165] op_sel_hi:[1,0]
	v_pk_mul_f32 v[18:19], v[18:19], v[164:165] op_sel_hi:[1,0]
	v_cvt_pk_bf16_f32 v147, v36, v37
	v_cvt_pk_bf16_f32 v148, v38, v39
	v_cvt_pk_bf16_f32 v149, v40, v41
	v_cvt_pk_bf16_f32 v142, v42, v43
	v_cvt_pk_bf16_f32 v143, v44, v45
	v_cvt_pk_bf16_f32 v144, v46, v47
	v_cvt_pk_bf16_f32 v145, v48, v49
	v_cvt_pk_bf16_f32 v134, v50, v51
	v_cvt_pk_bf16_f32 v135, v52, v53
	v_cvt_pk_bf16_f32 v136, v54, v55
	v_cvt_pk_bf16_f32 v137, v56, v57
	v_cvt_pk_bf16_f32 v138, v58, v59
	v_cvt_pk_bf16_f32 v139, v60, v61
	v_cvt_pk_bf16_f32 v140, v62, v63
	v_cvt_pk_bf16_f32 v141, v64, v65
	v_mul_f32_e32 v173, v173, v164
	v_add_f32_e32 v175, v34, v35
	v_mov_b32_e32 v164, v176
	v_cndmask_b32_e64 v34, 0, 1, s[2:3]
	v_cmp_ne_u32_e64 s[6:7], 1, v34
	s_andn2_b64 vcc, exec, s[2:3]
	s_cbranch_vccz .LBB0_89
	s_branch .LBB0_92

.LBB0_98:
	s_xor_b32 s0, s9, 2
	s_mulk_i32 s0, 0x6400
	v_add_f32_e32 v173, v175, v173
	v_add_u32_e32 v175, s0, v167
	ds_read_b128 v[34:37], v175
	ds_read_b128 v[38:41], v175 offset:32
	ds_read_b128 v[42:45], v175 offset:64
	v_add_u32_e32 v196, s14, v168
	ds_read_b128 v[46:49], v175 offset:96
	s_waitcnt lgkmcnt(3)
	v_mfma_f32_32x32x16_bf16 v[50:65], v[34:37], v[110:113], 0
	v_exp_f32_e32 v82, v82
	v_exp_f32_e32 v83, v83
	ds_read_b128 v[34:37], v175 offset:128
	s_waitcnt lgkmcnt(3)
	v_mfma_f32_32x32x16_bf16 v[50:65], v[38:41], v[114:117], v[50:65]
	v_exp_f32_e32 v84, v84
	v_exp_f32_e32 v85, v85
	ds_read_b128 v[38:41], v175 offset:160
	s_waitcnt lgkmcnt(3)
	v_mfma_f32_32x32x16_bf16 v[50:65], v[42:45], v[118:121], v[50:65]
	v_exp_f32_e32 v86, v86
	v_exp_f32_e32 v87, v87
	v_pk_add_f32 v[176:177], v[82:83], 0 op_sel_hi:[1,0]
	ds_read_b128 v[42:45], v175 offset:6656
	s_waitcnt lgkmcnt(3)
	v_mfma_f32_32x32x16_bf16 v[50:65], v[46:49], v[122:125], v[50:65]
	v_exp_f32_e32 v88, v88
	v_exp_f32_e32 v89, v89
	v_pk_add_f32 v[46:47], v[84:85], v[176:177]
	ds_read_b128 v[176:179], v175 offset:6688
	s_waitcnt lgkmcnt(3)
	v_mfma_f32_32x32x16_bf16 v[50:65], v[34:37], v[126:129], v[50:65]
	v_exp_f32_e32 v90, v90
	v_exp_f32_e32 v91, v91
	v_pk_add_f32 v[34:35], v[86:87], v[46:47]
	ds_read_b128 v[180:183], v175 offset:6720
	s_waitcnt lgkmcnt(3)
	v_mfma_f32_32x32x16_bf16 v[50:65], v[38:41], v[130:133], v[50:65]
	v_exp_f32_e32 v92, v92
	v_exp_f32_e32 v93, v93
	v_pk_add_f32 v[190:191], v[88:89], v[34:35]
	ds_read_b128 v[184:187], v175 offset:6752
	s_waitcnt lgkmcnt(3)
	v_mfma_f32_32x32x16_bf16 v[34:49], v[42:45], v[110:113], 0
	v_exp_f32_e32 v94, v94
	v_exp_f32_e32 v95, v95
	v_pk_add_f32 v[194:195], v[90:91], v[190:191]
	ds_read_b128 v[190:193], v175 offset:6784
	s_waitcnt lgkmcnt(3)
	v_mfma_f32_32x32x16_bf16 v[34:49], v[176:179], v[114:117], v[34:49]
	v_exp_f32_e32 v96, v96
	v_exp_f32_e32 v97, v97
	v_pk_add_f32 v[194:195], v[92:93], v[194:195]
	ds_read_b128 v[176:179], v175 offset:6816
	s_waitcnt lgkmcnt(3)
	v_mfma_f32_32x32x16_bf16 v[34:49], v[180:183], v[118:121], v[34:49]
	v_exp_f32_e32 v66, v66
	v_exp_f32_e32 v67, v67
	v_pk_add_f32 v[194:195], v[94:95], v[194:195]
	ds_read_b64_tr_b16 v[180:181], v196 offset:13312
	ds_read_b64_tr_b16 v[182:183], v196 offset:14848
	s_waitcnt lgkmcnt(4)
	v_mfma_f32_32x32x16_bf16 v[34:49], v[184:187], v[122:125], v[34:49]
	v_exp_f32_e32 v68, v68
	v_exp_f32_e32 v69, v69
	v_pk_add_f32 v[194:195], v[96:97], v[194:195]
	ds_read_b64_tr_b16 v[184:185], v196 offset:13376
	ds_read_b64_tr_b16 v[186:187], v196 offset:14912
	s_waitcnt lgkmcnt(5)
	v_mfma_f32_32x32x16_bf16 v[34:49], v[190:193], v[126:129], v[34:49]
	v_exp_f32_e32 v70, v70
	v_exp_f32_e32 v71, v71
	v_pk_add_f32 v[194:195], v[66:67], v[194:195]
	ds_read_b64_tr_b16 v[190:191], v196 offset:16384
	ds_read_b64_tr_b16 v[192:193], v196 offset:17920
	s_waitcnt lgkmcnt(6)
	v_mfma_f32_32x32x16_bf16 v[34:49], v[176:179], v[130:133], v[34:49]
	v_exp_f32_e32 v72, v72
	v_exp_f32_e32 v73, v73
	v_pk_add_f32 v[194:195], v[68:69], v[194:195]
	ds_read_b64_tr_b16 v[176:177], v196 offset:16448
	ds_read_b64_tr_b16 v[178:179], v196 offset:17984
	s_waitcnt lgkmcnt(6)
	v_mfma_f32_32x32x16_bf16 v[2:17], v[180:183], v[146:149], v[2:17]
	v_exp_f32_e32 v74, v74
	v_exp_f32_e32 v75, v75
	v_pk_add_f32 v[194:195], v[70:71], v[194:195]
	ds_read_b64_tr_b16 v[180:181], v196 offset:19456
	ds_read_b64_tr_b16 v[182:183], v196 offset:20992
	s_waitcnt lgkmcnt(6)
	v_mfma_f32_32x32x16_bf16 v[18:33], v[184:187], v[146:149], v[18:33]
	v_exp_f32_e32 v76, v76
	v_exp_f32_e32 v77, v77
	v_pk_add_f32 v[184:185], v[72:73], v[194:195]
	ds_read_b64_tr_b16 v[146:147], v196 offset:19520
	ds_read_b64_tr_b16 v[148:149], v196 offset:21056
	s_waitcnt lgkmcnt(6)
	v_mfma_f32_32x32x16_bf16 v[2:17], v[190:193], v[142:145], v[2:17]
	v_exp_f32_e32 v78, v78
	v_exp_f32_e32 v79, v79
	v_pk_add_f32 v[190:191], v[74:75], v[184:185]
	ds_read_b64_tr_b16 v[184:185], v196 offset:22528
	ds_read_b64_tr_b16 v[186:187], v196 offset:24064
	s_waitcnt lgkmcnt(6)
	v_mfma_f32_32x32x16_bf16 v[18:33], v[176:179], v[142:145], v[18:33]
	v_exp_f32_e32 v80, v80
	v_exp_f32_e32 v81, v81
	v_pk_add_f32 v[176:177], v[76:77], v[190:191]
	ds_read_b64_tr_b16 v[142:143], v196 offset:22592
	ds_read_b64_tr_b16 v[144:145], v196 offset:24128
	s_waitcnt lgkmcnt(6)
	v_mfma_f32_32x32x16_bf16 v[2:17], v[180:183], v[134:137], v[2:17]
	v_add_f32_e64 v176, v78, v176
	v_add_f32_e64 v177, v79, v177
	s_waitcnt lgkmcnt(4)
	v_mfma_f32_32x32x16_bf16 v[18:33], v[146:149], v[134:137], v[18:33]
	v_add_f32_e64 v134, v80, v176
	v_add_f32_e64 v135, v81, v177
	s_waitcnt lgkmcnt(2)
	v_mfma_f32_32x32x16_bf16 v[2:17], v[184:187], v[138:141], v[2:17]
	s_waitcnt lgkmcnt(0)
	v_mfma_f32_32x32x16_bf16 v[18:33], v[142:145], v[138:141], v[18:33]
	v_add_f32_e32 v175, v134, v135
	v_cmp_ngt_f32_e32 vcc, s82, v175
	s_cbranch_vccz .LBB0_100
	ds_read_b128 v[66:69], v174 offset:25600
	ds_read_b128 v[82:85], v174 offset:25632
	s_mov_b64 s[12:13], 0
	s_waitcnt lgkmcnt(1)
	v_mfma_f32_32x32x16_bf16 v[66:81], v[66:69], v[110:113], 0
	s_waitcnt lgkmcnt(0)
	v_mfma_f32_32x32x16_bf16 v[66:81], v[82:85], v[114:117], v[66:81]
	ds_read_b128 v[82:85], v174 offset:25664
	ds_read_b128 v[86:89], v174 offset:25696
	s_waitcnt lgkmcnt(1)
	v_mfma_f32_32x32x16_bf16 v[66:81], v[82:85], v[118:121], v[66:81]
	s_waitcnt lgkmcnt(0)
	v_mfma_f32_32x32x16_bf16 v[66:81], v[86:89], v[122:125], v[66:81]
	ds_read_b128 v[82:85], v174 offset:25728
	ds_read_b128 v[86:89], v174 offset:25760
	s_waitcnt lgkmcnt(1)
	v_mfma_f32_32x32x16_bf16 v[66:81], v[82:85], v[126:129], v[66:81]
	ds_read_b128 v[82:85], v174 offset:32256
	ds_read_b128 v[134:137], v174 offset:32288
	s_waitcnt lgkmcnt(2)
	v_mfma_f32_32x32x16_bf16 v[66:81], v[86:89], v[130:133], v[66:81]
	s_waitcnt lgkmcnt(1)
	v_mfma_f32_32x32x16_bf16 v[82:97], v[82:85], v[110:113], 0
	s_nop 9
	v_max3_f32 v142, v66, s33, v67
	s_waitcnt lgkmcnt(0)
	v_mfma_f32_32x32x16_bf16 v[82:97], v[134:137], v[114:117], v[82:97]
	ds_read_b128 v[134:137], v174 offset:32320
	ds_read_b128 v[138:141], v174 offset:32352
	s_waitcnt lgkmcnt(1)
	v_mfma_f32_32x32x16_bf16 v[82:97], v[134:137], v[118:121], v[82:97]
	s_waitcnt lgkmcnt(0)
	v_mfma_f32_32x32x16_bf16 v[82:97], v[138:141], v[122:125], v[82:97]
	ds_read_b128 v[134:137], v174 offset:32384
	ds_read_b128 v[138:141], v174 offset:32416
	s_waitcnt lgkmcnt(1)
	v_mfma_f32_32x32x16_bf16 v[82:97], v[134:137], v[126:129], v[82:97]
	v_max3_f32 v134, v142, v68, v69
	v_max3_f32 v134, v134, v70, v71
	v_max3_f32 v134, v134, v72, v73
	v_max3_f32 v134, v134, v74, v75
	v_max3_f32 v134, v134, v76, v77
	v_max3_f32 v134, v134, v78, v79
	v_max3_f32 v134, v134, v80, v81
	s_waitcnt lgkmcnt(0)
	v_mfma_f32_32x32x16_bf16 v[82:97], v[138:141], v[130:133], v[82:97]
	v_mov_b32_e32 v135, v220
	s_nop 0
	v_lshlrev_b32_e32 v135, 2, v135
	v_xor_b32_e32 v135, 0x80, v135
	s_nop 7
	v_max3_f32 v134, v134, v82, v83
	v_max3_f32 v134, v134, v84, v85
	v_max3_f32 v134, v134, v86, v87
	v_max3_f32 v134, v134, v88, v89
	v_max3_f32 v134, v134, v90, v91
	v_max3_f32 v134, v134, v92, v93
	v_max3_f32 v134, v134, v94, v95
	v_max3_f32 v134, v134, v96, v97
	ds_bpermute_b32 v135, v135, v134
	s_waitcnt lgkmcnt(0)
	v_max3_f32 v174, v164, v134, v135
	v_pk_add_f32 v[66:67], v[66:67], v[174:175] op_sel_hi:[1,0] neg_lo:[0,1] neg_hi:[0,1]
	v_pk_add_f32 v[68:69], v[68:69], v[174:175] op_sel_hi:[1,0] neg_lo:[0,1] neg_hi:[0,1]
	v_exp_f32_e32 v66, v66
	v_exp_f32_e32 v67, v67
	v_pk_add_f32 v[70:71], v[70:71], v[174:175] op_sel_hi:[1,0] neg_lo:[0,1] neg_hi:[0,1]
	v_exp_f32_e32 v68, v68
	v_exp_f32_e32 v69, v69
	v_pk_add_f32 v[72:73], v[72:73], v[174:175] op_sel_hi:[1,0] neg_lo:[0,1] neg_hi:[0,1]
	v_exp_f32_e32 v70, v70
	v_exp_f32_e32 v71, v71
	v_sub_f32_e32 v134, v164, v174
	v_pk_add_f32 v[74:75], v[74:75], v[174:175] op_sel_hi:[1,0] neg_lo:[0,1] neg_hi:[0,1]
	v_exp_f32_e32 v72, v72
	v_exp_f32_e32 v73, v73
	v_exp_f32_e32 v164, v134
	v_pk_add_f32 v[76:77], v[76:77], v[174:175] op_sel_hi:[1,0] neg_lo:[0,1] neg_hi:[0,1]
	v_exp_f32_e32 v74, v74
	v_exp_f32_e32 v75, v75
	v_pk_add_f32 v[134:135], v[66:67], 0 op_sel_hi:[1,0]
	v_pk_add_f32 v[78:79], v[78:79], v[174:175] op_sel_hi:[1,0] neg_lo:[0,1] neg_hi:[0,1]
	v_exp_f32_e32 v76, v76
	v_exp_f32_e32 v77, v77
	v_cvt_pk_bf16_f32 v142, v66, v67
	v_pk_add_f32 v[66:67], v[68:69], v[134:135]
	v_pk_add_f32 v[80:81], v[80:81], v[174:175] op_sel_hi:[1,0] neg_lo:[0,1] neg_hi:[0,1]
	v_exp_f32_e32 v78, v78
	v_exp_f32_e32 v79, v79
	v_pk_add_f32 v[66:67], v[70:71], v[66:67]
	v_pk_add_f32 v[82:83], v[82:83], v[174:175] op_sel_hi:[1,0] neg_lo:[0,1] neg_hi:[0,1]
	v_exp_f32_e32 v80, v80
	v_exp_f32_e32 v81, v81
	v_pk_add_f32 v[66:67], v[72:73], v[66:67]
	v_pk_add_f32 v[84:85], v[84:85], v[174:175] op_sel_hi:[1,0] neg_lo:[0,1] neg_hi:[0,1]
	v_exp_f32_e32 v82, v82
	v_exp_f32_e32 v83, v83
	v_pk_add_f32 v[66:67], v[74:75], v[66:67]
	v_pk_add_f32 v[86:87], v[86:87], v[174:175] op_sel_hi:[1,0] neg_lo:[0,1] neg_hi:[0,1]
	v_exp_f32_e32 v84, v84
	v_exp_f32_e32 v85, v85
	v_pk_add_f32 v[66:67], v[76:77], v[66:67]
	v_pk_add_f32 v[88:89], v[88:89], v[174:175] op_sel_hi:[1,0] neg_lo:[0,1] neg_hi:[0,1]
	v_exp_f32_e32 v86, v86
	v_exp_f32_e32 v87, v87
	v_pk_add_f32 v[66:67], v[78:79], v[66:67]
	v_pk_add_f32 v[90:91], v[90:91], v[174:175] op_sel_hi:[1,0] neg_lo:[0,1] neg_hi:[0,1]
	v_exp_f32_e32 v88, v88
	v_exp_f32_e32 v89, v89
	v_pk_add_f32 v[66:67], v[80:81], v[66:67]
	v_pk_add_f32 v[92:93], v[92:93], v[174:175] op_sel_hi:[1,0] neg_lo:[0,1] neg_hi:[0,1]
	v_exp_f32_e32 v90, v90
	v_exp_f32_e32 v91, v91
	v_pk_add_f32 v[66:67], v[82:83], v[66:67]
	v_pk_add_f32 v[94:95], v[94:95], v[174:175] op_sel_hi:[1,0] neg_lo:[0,1] neg_hi:[0,1]
	v_exp_f32_e32 v92, v92
	v_exp_f32_e32 v93, v93
	v_pk_add_f32 v[66:67], v[84:85], v[66:67]
	v_pk_add_f32 v[96:97], v[96:97], v[174:175] op_sel_hi:[1,0] neg_lo:[0,1] neg_hi:[0,1]
	v_exp_f32_e32 v94, v94
	v_exp_f32_e32 v95, v95
	v_pk_add_f32 v[66:67], v[86:87], v[66:67]
	v_exp_f32_e32 v96, v96
	v_exp_f32_e32 v97, v97
	v_pk_add_f32 v[66:67], v[88:89], v[66:67]
	v_pk_mul_f32 v[16:17], v[16:17], v[164:165] op_sel_hi:[1,0]
	v_pk_add_f32 v[66:67], v[90:91], v[66:67]
	v_pk_mul_f32 v[14:15], v[14:15], v[164:165] op_sel_hi:[1,0]
	v_pk_add_f32 v[66:67], v[92:93], v[66:67]
	v_pk_mul_f32 v[12:13], v[12:13], v[164:165] op_sel_hi:[1,0]
	v_pk_add_f32 v[66:67], v[94:95], v[66:67]
	v_pk_mul_f32 v[10:11], v[10:11], v[164:165] op_sel_hi:[1,0]
	v_pk_add_f32 v[66:67], v[96:97], v[66:67]
	v_pk_mul_f32 v[8:9], v[8:9], v[164:165] op_sel_hi:[1,0]
	v_pk_mul_f32 v[6:7], v[6:7], v[164:165] op_sel_hi:[1,0]
	v_pk_mul_f32 v[4:5], v[4:5], v[164:165] op_sel_hi:[1,0]
	v_pk_mul_f32 v[2:3], v[2:3], v[164:165] op_sel_hi:[1,0]
	v_pk_mul_f32 v[32:33], v[32:33], v[164:165] op_sel_hi:[1,0]
	v_pk_mul_f32 v[30:31], v[30:31], v[164:165] op_sel_hi:[1,0]
	v_pk_mul_f32 v[28:29], v[28:29], v[164:165] op_sel_hi:[1,0]
	v_pk_mul_f32 v[26:27], v[26:27], v[164:165] op_sel_hi:[1,0]
	v_pk_mul_f32 v[24:25], v[24:25], v[164:165] op_sel_hi:[1,0]
	v_pk_mul_f32 v[22:23], v[22:23], v[164:165] op_sel_hi:[1,0]
	v_pk_mul_f32 v[20:21], v[20:21], v[164:165] op_sel_hi:[1,0]
	v_pk_mul_f32 v[18:19], v[18:19], v[164:165] op_sel_hi:[1,0]
	v_cvt_pk_bf16_f32 v143, v68, v69
	v_cvt_pk_bf16_f32 v144, v70, v71
	v_cvt_pk_bf16_f32 v145, v72, v73
	v_cvt_pk_bf16_f32 v146, v74, v75
	v_cvt_pk_bf16_f32 v147, v76, v77
	v_cvt_pk_bf16_f32 v148, v78, v79
	v_cvt_pk_bf16_f32 v149, v80, v81
	v_cvt_pk_bf16_f32 v134, v82, v83
	v_cvt_pk_bf16_f32 v135, v84, v85
	v_cvt_pk_bf16_f32 v136, v86, v87
	v_cvt_pk_bf16_f32 v137, v88, v89
	v_cvt_pk_bf16_f32 v138, v90, v91
	v_cvt_pk_bf16_f32 v139, v92, v93
	v_cvt_pk_bf16_f32 v140, v94, v95
	v_cvt_pk_bf16_f32 v141, v96, v97
	v_mul_f32_e32 v173, v173, v164
	v_add_f32_e32 v175, v66, v67
	v_mov_b32_e32 v164, v174
	s_and_b64 vcc, exec, s[6:7]
	s_cbranch_vccnz .LBB0_79
	s_branch .LBB0_101

; #define LAS __attribute__((address_space(3)))
; __device__ __forceinline__ unsigned cvt_pk_bf16(float lo, float hi) { const f32x2_ v = {lo, hi}; return __builtin_bit_cast(unsigned, __builtin_convertvector(v, bf16x2_)); }
; __device__ __forceinline__ float fast_exp2(float x) { return __builtin_amdgcn_exp2f(x); }
; #define MFMA32(a, b, c) __builtin_amdgcn_mfma_f32_32x32x16_bf16((a), (b), (c), 0, 0, 0)
; template <int MODE>
; __device__ __forceinline__ void attn_item(PK p, int l, LAS unsigned char* lds, int b, int h, int qb, bool ctxq, float lam, float lam_init) {
;     ...
;             if (PIPE) {
;                 LAS unsigned char* _vb = lds + pbuf * BUFSZ + KBUF + voff;
;                 f32x2 _rs[NCOMP]; u32x4 _pk[NCOMP][2][2];
; #pragma unroll
;                 for (int c = 0; c < NCOMP; ++c) _rs[c] = (f32x2){0.f, 0.f};
;                 bf16x8 _vf[10];
;     ...
;                 VLOAD_(_vf[0], 0); VLOAD_(_vf[1], 1);
;                 __builtin_amdgcn_sched_barrier(0);
; #pragma unroll
;                 for (int i = 0; i < 17; ++i) {
;                     if (i < 16 && (i & 1) == 0) VLOAD_(_vf[(i >> 1) + 2], (i >> 1) + 2);
;                     if (i < 16) { const int v = i >> 1, c = (NCOMP == 2) ? (i & 1) : 0, kt = v >> 2, s2 = (v >> 1) & 1, dt = v & 1; O[c][dt] = MFMA32(_vf[v], Pold[c][kt][s2], O[c][dt]); }
;                     if (i < 16) {
; #pragma unroll
;                         for (int q2 = 0; q2 < 4; ++q2) { const int idx = 4 * i + q2, c = (idx >> 5) % NCOMP, kt = (idx >> 4) & 1, r = idx & 15; S[c][kt][r] = fast_exp2(S[c][kt][r]); } }
;                     if (i >= 1) {
; #pragma unroll
;                         for (int q2 = 0; q2 < 2; ++q2) { const int j = 2 * (i - 1) + q2, c = (j >> 4) % NCOMP, kt = (j >> 3) & 1, s2 = (j >> 2) & 1, e = j & 3;
;                             const f32x2 ev = (f32x2){S[c][kt][8 * s2 + 2 * e], S[c][kt][8 * s2 + 2 * e + 1]}; _rs[c] += ev; _pk[c][kt][s2][e] = cvt_pk_bf16(ev.x, ev.y); } }
;                     __builtin_amdgcn_sched_barrier(0);
;                 }
;     ...
; #pragma unroll
;                 for (int c = 0; c < NCOMP; ++c) { mxc[c] = _rs[c].x + _rs[c].y;
; #pragma unroll
;                     for (int kt = 0; kt < 2; ++kt)
; #pragma unroll
;                         for (int s2 = 0; s2 < 2; ++s2) P[c][kt][s2] = __builtin_bit_cast(bf16x8, _pk[c][kt][s2]); }
.LBB0_117:
	s_mul_i32 s0, s18, 0x5400
	v_add_u32_e32 v1, s0, v237
	ds_read_b64_tr_b16 v[190:191], v1 offset:9216
	ds_read_b64_tr_b16 v[192:193], v1 offset:10752
	ds_read_b64_tr_b16 v[196:197], v1 offset:10816
	ds_read_b64_tr_b16 v[194:195], v1 offset:9280
	ds_read_b64_tr_b16 v[214:215], v1 offset:12288
	ds_read_b64_tr_b16 v[216:217], v1 offset:13824
	s_waitcnt lgkmcnt(4)
	v_mfma_f32_32x32x16_bf16 v[52:67], v[190:193], v[176:179], v[52:67]
	v_exp_f32_e32 v116, v116
	v_exp_f32_e32 v117, v117
	v_exp_f32_e32 v118, v118
	v_exp_f32_e32 v119, v119
	v_mfma_f32_32x32x16_bf16 v[36:51], v[190:193], v[184:187], v[36:51]
	v_exp_f32_e32 v120, v120
	v_exp_f32_e32 v121, v121
	v_exp_f32_e32 v122, v122
	v_exp_f32_e32 v123, v123
	v_pk_add_f32 v[2:3], v[116:117], 0 op_sel_hi:[1,0]
	s_nop 0
	v_pk_add_f32 v[2:3], v[118:119], v[2:3]
	ds_read_b64_tr_b16 v[190:191], v1 offset:12352
	ds_read_b64_tr_b16 v[192:193], v1 offset:13888
	s_waitcnt lgkmcnt(4)
	v_mfma_f32_32x32x16_bf16 v[20:35], v[194:197], v[176:179], v[20:35]
	v_exp_f32_e32 v124, v124
	v_exp_f32_e32 v125, v125
	v_exp_f32_e32 v126, v126
	v_exp_f32_e32 v127, v127
	v_pk_add_f32 v[2:3], v[120:121], v[2:3]
	s_nop 0
	v_pk_add_f32 v[2:3], v[122:123], v[2:3]
	v_mfma_f32_32x32x16_bf16 v[4:19], v[194:197], v[184:187], v[4:19]
	v_exp_f32_e32 v128, v128
	v_exp_f32_e32 v129, v129
	v_exp_f32_e32 v130, v130
	v_exp_f32_e32 v131, v131
	v_pk_add_f32 v[2:3], v[124:125], v[2:3]
	s_nop 0
	v_pk_add_f32 v[2:3], v[126:127], v[2:3]
	ds_read_b64_tr_b16 v[194:195], v1 offset:15360
	ds_read_b64_tr_b16 v[196:197], v1 offset:16896
	s_waitcnt lgkmcnt(4)
	v_mfma_f32_32x32x16_bf16 v[52:67], v[214:217], v[172:175], v[52:67]
	v_exp_f32_e32 v100, v100
	v_exp_f32_e32 v101, v101
	v_exp_f32_e32 v102, v102
	v_exp_f32_e32 v103, v103
	v_pk_add_f32 v[2:3], v[128:129], v[2:3]
	s_nop 0
	v_pk_add_f32 v[2:3], v[130:131], v[2:3]
	v_mfma_f32_32x32x16_bf16 v[36:51], v[214:217], v[180:183], v[36:51]
	v_exp_f32_e32 v104, v104
	v_exp_f32_e32 v105, v105
	v_exp_f32_e32 v106, v106
	v_exp_f32_e32 v107, v107
	v_pk_add_f32 v[2:3], v[100:101], v[2:3]
	s_nop 0
	v_pk_add_f32 v[2:3], v[102:103], v[2:3]
	ds_read_b64_tr_b16 v[214:215], v1 offset:15424
	ds_read_b64_tr_b16 v[216:217], v1 offset:16960
	s_waitcnt lgkmcnt(4)
	v_mfma_f32_32x32x16_bf16 v[20:35], v[190:193], v[172:175], v[20:35]
	v_exp_f32_e32 v108, v108
	v_exp_f32_e32 v109, v109
	v_exp_f32_e32 v110, v110
	v_exp_f32_e32 v111, v111
	v_pk_add_f32 v[2:3], v[104:105], v[2:3]
	s_nop 0
	v_pk_add_f32 v[2:3], v[106:107], v[2:3]
	v_mfma_f32_32x32x16_bf16 v[4:19], v[190:193], v[180:183], v[4:19]
	v_exp_f32_e32 v112, v112
	v_exp_f32_e32 v113, v113
	v_exp_f32_e32 v114, v114
	v_exp_f32_e32 v115, v115
	v_pk_add_f32 v[2:3], v[108:109], v[2:3]
	s_nop 0
	v_pk_add_f32 v[2:3], v[110:111], v[2:3]
	ds_read_b64_tr_b16 v[190:191], v1 offset:18432
	ds_read_b64_tr_b16 v[192:193], v1 offset:19968
	s_waitcnt lgkmcnt(4)
	v_mfma_f32_32x32x16_bf16 v[52:67], v[194:197], v[144:147], v[52:67]
	v_exp_f32_e32 v84, v84
	v_exp_f32_e32 v85, v85
	v_exp_f32_e32 v86, v86
	v_exp_f32_e32 v87, v87
	v_pk_add_f32 v[2:3], v[112:113], v[2:3]
	s_nop 0
	v_pk_add_f32 v[2:3], v[114:115], v[2:3]
	v_mfma_f32_32x32x16_bf16 v[36:51], v[194:197], v[164:167], v[36:51]
	v_exp_f32_e32 v88, v88
	v_exp_f32_e32 v89, v89
	v_exp_f32_e32 v90, v90
	v_exp_f32_e32 v91, v91
	v_pk_add_f32 v[194:195], v[84:85], 0 op_sel_hi:[1,0]
	s_nop 0
	v_pk_add_f32 v[198:199], v[86:87], v[194:195]
	ds_read_b64_tr_b16 v[194:195], v1 offset:18496
	ds_read_b64_tr_b16 v[196:197], v1 offset:20032
	s_waitcnt lgkmcnt(4)
	v_mfma_f32_32x32x16_bf16 v[20:35], v[214:217], v[144:147], v[20:35]
	v_exp_f32_e32 v92, v92
	v_exp_f32_e32 v93, v93
	v_exp_f32_e32 v94, v94
	v_exp_f32_e32 v95, v95
	v_pk_add_f32 v[198:199], v[88:89], v[198:199]
	s_nop 0
	v_pk_add_f32 v[198:199], v[90:91], v[198:199]
	v_mfma_f32_32x32x16_bf16 v[4:19], v[214:217], v[164:167], v[4:19]
	v_exp_f32_e32 v96, v96
	v_exp_f32_e32 v97, v97
	v_exp_f32_e32 v98, v98
	v_exp_f32_e32 v99, v99
	v_pk_add_f32 v[198:199], v[92:93], v[198:199]
	s_nop 0
	v_pk_add_f32 v[198:199], v[94:95], v[198:199]
	s_waitcnt lgkmcnt(2)
	v_mfma_f32_32x32x16_bf16 v[52:67], v[190:193], v[148:151], v[52:67]
	v_exp_f32_e32 v68, v68
	v_exp_f32_e32 v69, v69
	v_exp_f32_e32 v70, v70
	v_exp_f32_e32 v71, v71
	v_pk_add_f32 v[198:199], v[96:97], v[198:199]
	s_nop 0
	v_pk_add_f32 v[198:199], v[98:99], v[198:199]
	v_mfma_f32_32x32x16_bf16 v[36:51], v[190:193], v[140:143], v[36:51]
	v_exp_f32_e32 v72, v72
	v_exp_f32_e32 v73, v73
	v_exp_f32_e32 v74, v74
	v_exp_f32_e32 v75, v75
	v_pk_add_f32 v[190:191], v[68:69], v[198:199]
	s_nop 0
	v_pk_add_f32 v[190:191], v[70:71], v[190:191]
	s_waitcnt lgkmcnt(0)
	v_mfma_f32_32x32x16_bf16 v[20:35], v[194:197], v[148:151], v[20:35]
	v_exp_f32_e32 v76, v76
	v_exp_f32_e32 v77, v77
	v_exp_f32_e32 v78, v78
	v_exp_f32_e32 v79, v79
	v_pk_add_f32 v[190:191], v[72:73], v[190:191]
	s_nop 0
	v_pk_add_f32 v[190:191], v[74:75], v[190:191]
	v_mfma_f32_32x32x16_bf16 v[4:19], v[194:197], v[140:143], v[4:19]
	v_exp_f32_e32 v80, v80
	v_exp_f32_e32 v81, v81
	v_exp_f32_e32 v82, v82
	v_exp_f32_e32 v83, v83
	v_pk_add_f32 v[190:191], v[76:77], v[190:191]
	s_nop 0
	v_pk_add_f32 v[190:191], v[78:79], v[190:191]
	s_nop 0
	v_pk_add_f32 v[190:191], v[80:81], v[190:191]
	s_nop 0
	v_pk_add_f32 v[190:191], v[82:83], v[190:191]
	v_mov_b32_e32 v192, v2
	v_mov_b32_e32 v193, v190
	v_mov_b32_e32 v190, v3
	v_pk_add_f32 v[214:215], v[192:193], v[190:191]
	s_and_b64 vcc, exec, s[14:15]
	s_mov_b64 s[0:1], -1
	s_cbranch_vccz .LBB0_120
	v_cmp_ngt_f32_e32 vcc, s82, v214
	v_cmp_ngt_f32_e64 s[4:5], s82, v215
	s_or_b64 vcc, vcc, s[4:5]
	v_cndmask_b32_e64 v1, 0, 1, vcc
	v_cmp_ne_u32_e64 s[4:5], 0, v1
	s_cmp_eq_u64 s[4:5], 0
	s_mov_b32 s14, 0
	s_cselect_b64 s[0:1], -1, 0
	s_cbranch_vccz .LBB0_120
	v_mov_b32_e32 v2, v0
	v_mov_b32_e32 v3, v0
	v_mov_b32_e32 v1, v0
	v_mov_b64_e32 v[142:143], v[2:3]
	v_mov_b64_e32 v[166:167], v[2:3]
	v_mov_b64_e32 v[182:183], v[2:3]
	v_mov_b64_e32 v[186:187], v[2:3]
	v_mov_b64_e32 v[150:151], v[2:3]
	v_mov_b64_e32 v[146:147], v[2:3]
	v_mov_b64_e32 v[174:175], v[2:3]
	v_mov_b64_e32 v[178:179], v[2:3]
	s_mov_b32 s14, 41
	v_mov_b64_e32 v[140:141], v[0:1]
	v_mov_b64_e32 v[164:165], v[0:1]
	v_mov_b64_e32 v[180:181], v[0:1]
	v_mov_b64_e32 v[184:185], v[0:1]
	v_mov_b64_e32 v[148:149], v[0:1]
	v_mov_b64_e32 v[144:145], v[0:1]
	v_mov_b64_e32 v[172:173], v[0:1]
	v_mov_b64_e32 v[176:177], v[0:1]
